# GEMM4 tile-loop header: compiler's conservative vmcnt(0) (waits for epilogue store acks) removed
# baseline (speedup 1.0000x reference)
.LBB0_1179:
	s_ashr_i32 s17, s16, 31
	s_lshl_b64 s[20:21], s[16:17], 19
	v_readlane_b32 s38, v251, 6
	v_readlane_b32 s39, v251, 7
	s_add_u32 s20, s38, s20
	s_addc_u32 s21, s39, s21
	s_and_b64 s[0:1], s[0:1], exec
	s_cselect_b32 s17, s21, s63
	s_cselect_b32 s93, s20, s62
	s_add_u32 vcc_lo, s62, 0x100
	v_mov_b32_e32 v14, 0
	s_addc_u32 vcc_hi, s63, 0
	s_mov_b32 s38, -2
	v_mov_b32_e32 v15, v14
	v_mov_b32_e32 v16, v14
	v_mov_b32_e32 v17, v14
	v_mov_b32_e32 v46, v14
	v_mov_b32_e32 v47, v14
	v_mov_b32_e32 v48, v14
	v_mov_b32_e32 v49, v14
	v_mov_b32_e32 v2, v14
	v_mov_b32_e32 v3, v14
	v_mov_b32_e32 v4, v14
	v_mov_b32_e32 v5, v14
	v_mov_b32_e32 v38, v14
	v_mov_b32_e32 v39, v14
	v_mov_b32_e32 v40, v14
	v_mov_b32_e32 v41, v14
	v_mov_b32_e32 v66, v14
	s_nop 0
	v_mov_b32_e32 v67, v14
	v_mov_b32_e32 v68, v14
	v_mov_b32_e32 v69, v14
	v_mov_b32_e32 v70, v14
	v_mov_b32_e32 v71, v14
	v_mov_b32_e32 v72, v14
	v_mov_b32_e32 v73, v14
	v_mov_b32_e32 v74, v14
	v_mov_b32_e32 v75, v14
	v_mov_b32_e32 v76, v14
	v_mov_b32_e32 v77, v14
	v_mov_b32_e32 v78, v14
	v_mov_b32_e32 v79, v14
	v_mov_b32_e32 v80, v14
	v_mov_b32_e32 v81, v14
	v_mov_b32_e32 v10, v14
	v_mov_b32_e32 v11, v14
	v_mov_b32_e32 v12, v14
	v_mov_b32_e32 v13, v14
	v_mov_b32_e32 v42, v14
	v_mov_b32_e32 v43, v14
	v_mov_b32_e32 v44, v14
	v_mov_b32_e32 v45, v14
	v_mov_b32_e32 v6, v14
	v_mov_b32_e32 v7, v14
	v_mov_b32_e32 v8, v14
	v_mov_b32_e32 v9, v14
	v_mov_b32_e32 v34, v14
	v_mov_b32_e32 v35, v14
	v_mov_b32_e32 v36, v14
	v_mov_b32_e32 v37, v14
	v_mov_b32_e32 v82, v14
	v_mov_b32_e32 v83, v14
	v_mov_b32_e32 v84, v14
	v_mov_b32_e32 v85, v14
	v_mov_b32_e32 v86, v14
	v_mov_b32_e32 v87, v14
	v_mov_b32_e32 v88, v14
	v_mov_b32_e32 v89, v14
	v_mov_b32_e32 v90, v14
	v_mov_b32_e32 v91, v14
	v_mov_b32_e32 v92, v14
	v_mov_b32_e32 v93, v14
	v_mov_b32_e32 v94, v14
	v_mov_b32_e32 v95, v14
	v_mov_b32_e32 v96, v14
	v_mov_b32_e32 v97, v14
	v_mov_b32_e32 v26, v14
	v_mov_b32_e32 v27, v14
	v_mov_b32_e32 v28, v14
	v_mov_b32_e32 v29, v14
	v_mov_b32_e32 v58, v14
	v_mov_b32_e32 v59, v14
	v_mov_b32_e32 v60, v14
	v_mov_b32_e32 v61, v14
	v_mov_b32_e32 v18, v14
	v_mov_b32_e32 v19, v14
	v_mov_b32_e32 v20, v14
	v_mov_b32_e32 v21, v14
	v_mov_b32_e32 v30, v14
	v_mov_b32_e32 v31, v14
	v_mov_b32_e32 v32, v14
	v_mov_b32_e32 v33, v14
	v_mov_b32_e32 v98, v14
	v_mov_b32_e32 v99, v14
	v_mov_b32_e32 v100, v14
	v_mov_b32_e32 v101, v14
	v_mov_b32_e32 v102, v14
	v_mov_b32_e32 v103, v14
	v_mov_b32_e32 v104, v14
	v_mov_b32_e32 v105, v14
	v_mov_b32_e32 v106, v14
	v_mov_b32_e32 v107, v14
	v_mov_b32_e32 v108, v14
	v_mov_b32_e32 v109, v14
	v_mov_b32_e32 v110, v14
	v_mov_b32_e32 v111, v14
	v_mov_b32_e32 v112, v14
	v_mov_b32_e32 v113, v14
	v_mov_b32_e32 v130, v14
	v_mov_b32_e32 v131, v14
	v_mov_b32_e32 v132, v14
	v_mov_b32_e32 v133, v14
	v_mov_b32_e32 v62, v14
	v_mov_b32_e32 v63, v14
	v_mov_b32_e32 v64, v14
	v_mov_b32_e32 v65, v14
	v_mov_b32_e32 v22, v14
	v_mov_b32_e32 v23, v14
	v_mov_b32_e32 v24, v14
	v_mov_b32_e32 v25, v14
	v_mov_b32_e32 v50, v14
	v_mov_b32_e32 v51, v14
	v_mov_b32_e32 v52, v14
	v_mov_b32_e32 v53, v14
	v_mov_b32_e32 v114, v14
	v_mov_b32_e32 v115, v14
	v_mov_b32_e32 v116, v14
	v_mov_b32_e32 v117, v14
	v_mov_b32_e32 v118, v14
	v_mov_b32_e32 v119, v14
	v_mov_b32_e32 v120, v14
	v_mov_b32_e32 v121, v14
	v_mov_b32_e32 v122, v14
	v_mov_b32_e32 v123, v14
	v_mov_b32_e32 v124, v14
	v_mov_b32_e32 v125, v14
	v_mov_b32_e32 v126, v14
	v_mov_b32_e32 v127, v14
	v_mov_b32_e32 v128, v14
	v_mov_b32_e32 v129, v14
